# idle workgroups of the G2 and down0 split-K tail rounds also run weight-conversion jobs (phase 5 fillers relieved)
# speedup vs baseline: 1.0109x; 1.0063x over previous
.LBB0_731:
	s_cmp_eq_u32 s28, 3
	s_cbranch_scc1 .Lfx_ph3
	s_cmp_eq_u32 s28, 6
	s_cbranch_scc1 .Lfx_ph6
	s_andn2_b64 vcc, exec, s[6:7]
	s_cbranch_vccnz .LBB0_804
	s_cmp_eq_u32 s28, 9
	s_movk_i32 s6, 0x7000
	s_mov_b32 s7, 0xb000
	s_cselect_b32 s6, s6, 0x9000
	s_cselect_b32 s7, 0x9000, s7
	s_cmp_eq_u32 s28, 5
	s_cselect_b32 s8, 0x4a00, s6
	s_cselect_b32 s9, 0x6c00, s7
	s_and_b64 s[6:7], exec, s[36:37]
	s_cselect_b32 s30, 0x1800, s8
	s_cselect_b32 s34, 0x4000, s9
	s_branch .Lfx_go
.Lfx_ph3:
	s_movk_i32 s30, 0x4000
	s_movk_i32 s34, 0x4a00
	s_movk_i32 s83, 0x60
	s_branch .Lfx_chk
.Lfx_ph6:
	s_movk_i32 s30, 0x6c00
	s_movk_i32 s34, 0x7000
	s_movk_i32 s83, 0xc0
.Lfx_chk:
	s_cmpk_lg_i32 s3, 0x100
	s_cbranch_scc1 .LBB0_804
.Lfx_go:
	s_mov_b64 s[6:7], -1
	s_and_b64 vcc, exec, s[38:39]
	s_cbranch_vccz .LBB0_769
	s_cmp_lt_i32 s2, s83
	s_cbranch_scc1 .LBB0_768
	s_mov_b64 s[6:7], s[0:1]
	s_mov_b32 s8, s2
	s_mov_b32 s12, s3
	v_mov_b32_e32 v0, v222
	s_sub_i32 s8, s8, s83
	s_lshl_b32 s8, s8, 3
	v_readfirstlane_b32 s9, v0
	s_ashr_i32 s9, s9, 6
	s_add_i32 s8, s8, s30
	s_add_i32 s35, s8, s9
	s_cmp_ge_i32 s35, s34
	s_cbranch_scc1 .LBB0_768
	s_load_dwordx2 s[8:9], s[6:7], 0xc8
	s_sub_i32 s12, s12, s83
	s_lshl_b32 s36, s12, 3
	v_and_b32_e32 v0, 63, v0
	v_lshlrev_b32_e32 v192, 2, v0
	s_waitcnt lgkmcnt(0)
	s_add_u32 s16, s8, 0x9000000
	s_addc_u32 s17, s9, 0
	s_add_u32 s18, s8, 0x7000000
	s_addc_u32 s19, s9, 0
	s_add_u32 s20, s8, 0x6000000
	s_addc_u32 s21, s9, 0
	s_add_u32 s22, s8, 0x4000000
	s_addc_u32 s23, s9, 0
	s_add_u32 s24, s8, 0x2000000
	s_addc_u32 s25, s9, 0
	s_add_u32 s26, s8, 0x1800000
	s_addc_u32 s27, s9, 0
	s_branch .LBB0_737
